# adds: in-projection forget-gate epilogue loads its 6 bias values once and no longer drains the store queue before every element (was 48 serialized load+store round trips on one wave per tile column 19
# speedup vs baseline: 1.0216x; 1.0029x over previous
; __device__ __forceinline__ float fexp2(float x) { return __builtin_amdgcn_exp2f(x); }
; __device__ __forceinline__ float flog2(float x) { return __builtin_amdgcn_logf(x); }
;     __device__ __forceinline__ void operator()(AccRef acc, const pg8::Unit& u, int wr, int wc, int fr, int fq) const {
;     ...
;         if (G == 78) {
;             if (fq == 0) {
; #pragma unroll
;                 for (int ai = 0; ai < 2; ++ai)
; #pragma unroll
;                     for (int m = 0; m < 4; ++m) {
;                         const int row = row0 + ai * 128 + m * 16;
;                         const float rsr = rst[row & 255];
; #pragma unroll
;                         for (int e = 0; e < 6; ++e) {
;                             const float x = acc[ai][0][m][e >> 2][e & 3] * rsr + fb[e];
;                             const float ls = fminf(x, 0.f) - LN2 * flog2(1.0f + fexp2(-fabsf(x) * LOG2E));
;                             logf[(size_t)row * 8 + e] = ls;
;                         }
;                     }
;             }
.LBB0_253:
	s_and_b64 vcc, exec, s[10:11]
	v_readlane_b32 s22, v255, 18
	v_readlane_b32 s23, v255, 19
	s_mov_b64 s[24:25], s[74:75]
	s_mov_b64 s[74:75], s[50:51]
	s_mov_b64 s[50:51], s[46:47]
	s_mov_b64 s[46:47], s[16:17]
	s_mov_b64 s[16:17], s[48:49]
	s_mov_b64 s[48:49], s[68:69]
	s_mov_b64 s[68:69], s[38:39]
	s_mov_b32 s39, s77
	s_cbranch_vccz .LBB0_257
	v_cmp_eq_u32_e32 vcc, 0, v244
	s_and_saveexec_b64 s[6:7], vcc
	s_cbranch_execz .LBB0_256
	v_readlane_b32 s10, v255, 45
	v_readlane_b32 s76, v255, 49
	v_readlane_b32 s11, v255, 46
	v_readlane_b32 s77, v255, 50
	s_add_u32 s10, s76, s10
	s_addc_u32 s11, s77, s11
	v_and_b32_e32 v2, 0xff, v19
	s_add_i32 s12, 0, 0x20100
	global_load_dword v8, v1, s[10:11]
	global_load_dword v9, v1, s[10:11] offset:4
	global_load_dword v10, v1, s[10:11] offset:8
	global_load_dword v11, v1, s[10:11] offset:12
	global_load_dword v12, v1, s[10:11] offset:16
	global_load_dword v13, v1, s[10:11] offset:20
	v_lshl_add_u32 v2, v2, 2, s12
	ds_read_b32 v4, v2
	s_mov_b32 s14, 0xbfb8aa3b
	v_ashrrev_i32_e32 v19, 31, v18
	v_readlane_b32 s20, v255, 37
	v_lshlrev_b64 v[2:3], 5, v[18:19]
	v_readlane_b32 s21, v255, 38
	v_readlane_b32 s78, v255, 51
	v_readlane_b32 s79, v255, 52
	v_lshl_add_u64 v[2:3], s[20:21], 0, v[2:3]
	s_waitcnt vmcnt(0) lgkmcnt(0)
	v_mov_b32_e32 v5, v8
	v_fmac_f32_e32 v5, v190, v4
	v_min_f32_e32 v6, 0, v5
	v_mul_f32_e64 v5, |v5|, s14
	v_exp_f32_e32 v5, v5
	s_nop 0
	v_add_f32_e32 v5, 1.0, v5
	v_log_f32_e32 v5, v5
	s_nop 0
	v_fmac_f32_e32 v6, 0xbf317218, v5
	global_store_dword v[2:3], v6, off
	v_mov_b32_e32 v5, v9
	v_fmac_f32_e32 v5, v191, v4
	v_min_f32_e32 v6, 0, v5
	v_mul_f32_e64 v5, |v5|, s14
	v_exp_f32_e32 v5, v5
	s_nop 0
	v_add_f32_e32 v5, 1.0, v5
	v_log_f32_e32 v5, v5
	s_nop 0
	v_fmac_f32_e32 v6, 0xbf317218, v5
	global_store_dword v[2:3], v6, off offset:4
	v_mov_b32_e32 v5, v10
	v_fmac_f32_e32 v5, v192, v4
	v_min_f32_e32 v6, 0, v5
	v_mul_f32_e64 v5, |v5|, s14
	v_exp_f32_e32 v5, v5
	s_nop 0
	v_add_f32_e32 v5, 1.0, v5
	v_log_f32_e32 v5, v5
	s_nop 0
	v_fmac_f32_e32 v6, 0xbf317218, v5
	global_store_dword v[2:3], v6, off offset:8
	v_mov_b32_e32 v5, v11
	v_fmac_f32_e32 v5, v193, v4
	v_min_f32_e32 v6, 0, v5
	v_mul_f32_e64 v5, |v5|, s14
	v_exp_f32_e32 v5, v5
	s_nop 0
	v_add_f32_e32 v5, 1.0, v5
	v_log_f32_e32 v5, v5
	s_nop 0
	v_fmac_f32_e32 v6, 0xbf317218, v5
	global_store_dword v[2:3], v6, off offset:12
	v_mov_b32_e32 v5, v12
	v_fmac_f32_e32 v5, v186, v4
	v_min_f32_e32 v6, 0, v5
	v_mul_f32_e64 v5, |v5|, s14
	v_exp_f32_e32 v5, v5
	s_nop 0
	v_add_f32_e32 v5, 1.0, v5
	v_log_f32_e32 v5, v5
	s_nop 0
	v_fmac_f32_e32 v6, 0xbf317218, v5
	global_store_dword v[2:3], v6, off offset:16
	v_mov_b32_e32 v5, v13
	v_fmac_f32_e32 v5, v187, v4
	v_min_f32_e32 v4, 0, v5
	v_mul_f32_e64 v5, |v5|, s14
	v_exp_f32_e32 v5, v5
	s_nop 0
	v_add_f32_e32 v5, 1.0, v5
	v_log_f32_e32 v5, v5
	s_nop 0
	v_fmac_f32_e32 v4, 0xbf317218, v5
	global_store_dword v[2:3], v4, off offset:20
	v_mov_b32_e32 v5, v8
	v_add_u32_e32 v2, 16, v18
	v_and_b32_e32 v3, 0xff, v2
	v_lshl_add_u32 v3, v3, 2, s12
	ds_read_b32 v4, v3
	v_ashrrev_i32_e32 v3, 31, v2
	v_lshlrev_b64 v[2:3], 5, v[2:3]
	v_lshl_add_u64 v[2:3], s[20:21], 0, v[2:3]
	s_waitcnt lgkmcnt(0)
	v_fmac_f32_e32 v5, v174, v4
	v_min_f32_e32 v6, 0, v5
	v_mul_f32_e64 v5, |v5|, s14
	v_exp_f32_e32 v5, v5
	s_nop 0
	v_add_f32_e32 v5, 1.0, v5
	v_log_f32_e32 v5, v5
	s_nop 0
	v_fmac_f32_e32 v6, 0xbf317218, v5
	global_store_dword v[2:3], v6, off
	v_mov_b32_e32 v5, v9
	v_fmac_f32_e32 v5, v175, v4
	v_min_f32_e32 v6, 0, v5
	v_mul_f32_e64 v5, |v5|, s14
	v_exp_f32_e32 v5, v5
	s_nop 0
	v_add_f32_e32 v5, 1.0, v5
	v_log_f32_e32 v5, v5
	s_nop 0
	v_fmac_f32_e32 v6, 0xbf317218, v5
	global_store_dword v[2:3], v6, off offset:4
	v_mov_b32_e32 v5, v10
	v_fmac_f32_e32 v5, v176, v4
	v_min_f32_e32 v6, 0, v5
	v_mul_f32_e64 v5, |v5|, s14
	v_exp_f32_e32 v5, v5
	s_nop 0
	v_add_f32_e32 v5, 1.0, v5
	v_log_f32_e32 v5, v5
	s_nop 0
	v_fmac_f32_e32 v6, 0xbf317218, v5
	global_store_dword v[2:3], v6, off offset:8
	v_mov_b32_e32 v5, v11
	v_fmac_f32_e32 v5, v177, v4
	v_min_f32_e32 v6, 0, v5
	v_mul_f32_e64 v5, |v5|, s14
	v_exp_f32_e32 v5, v5
	s_nop 0
	v_add_f32_e32 v5, 1.0, v5
	v_log_f32_e32 v5, v5
	s_nop 0
	v_fmac_f32_e32 v6, 0xbf317218, v5
	global_store_dword v[2:3], v6, off offset:12
	v_mov_b32_e32 v5, v12
	v_fmac_f32_e32 v5, v170, v4
	v_min_f32_e32 v6, 0, v5
	v_mul_f32_e64 v5, |v5|, s14
	v_exp_f32_e32 v5, v5
	s_nop 0
	v_add_f32_e32 v5, 1.0, v5
	v_log_f32_e32 v5, v5
	s_nop 0
	v_fmac_f32_e32 v6, 0xbf317218, v5
	global_store_dword v[2:3], v6, off offset:16
	v_mov_b32_e32 v5, v13
	v_fmac_f32_e32 v5, v171, v4
	v_min_f32_e32 v4, 0, v5
	v_mul_f32_e64 v5, |v5|, s14
	v_exp_f32_e32 v5, v5
	s_nop 0
	v_add_f32_e32 v5, 1.0, v5
	v_log_f32_e32 v5, v5
	s_nop 0
	v_fmac_f32_e32 v4, 0xbf317218, v5
	global_store_dword v[2:3], v4, off offset:20
	v_mov_b32_e32 v5, v8
	v_add_u32_e32 v2, 32, v18
	v_and_b32_e32 v3, 0xff, v2
	v_lshl_add_u32 v3, v3, 2, s12
	ds_read_b32 v4, v3
	v_ashrrev_i32_e32 v3, 31, v2
	v_lshlrev_b64 v[2:3], 5, v[2:3]
	v_lshl_add_u64 v[2:3], s[20:21], 0, v[2:3]
	s_waitcnt lgkmcnt(0)
; __device__ __forceinline__ float fexp2(float x) { return __builtin_amdgcn_exp2f(x); }
; __device__ __forceinline__ float flog2(float x) { return __builtin_amdgcn_logf(x); }
;     __device__ __forceinline__ void operator()(AccRef acc, const pg8::Unit& u, int wr, int wc, int fr, int fq) const {
;     ...
;         if (G == 78) {
;             if (fq == 0) {
; #pragma unroll
;                 for (int ai = 0; ai < 2; ++ai)
; #pragma unroll
;                     for (int m = 0; m < 4; ++m) {
;                         const int row = row0 + ai * 128 + m * 16;
;                         const float rsr = rst[row & 255];
; #pragma unroll
;                         for (int e = 0; e < 6; ++e) {
;                             const float x = acc[ai][0][m][e >> 2][e & 3] * rsr + fb[e];
;                             const float ls = fminf(x, 0.f) - LN2 * flog2(1.0f + fexp2(-fabsf(x) * LOG2E));
;                             logf[(size_t)row * 8 + e] = ls;
;                         }
;                     }
;             }
	v_fmac_f32_e32 v5, v158, v4
	v_min_f32_e32 v6, 0, v5
	v_mul_f32_e64 v5, |v5|, s14
	v_exp_f32_e32 v5, v5
	s_nop 0
	v_add_f32_e32 v5, 1.0, v5
	v_log_f32_e32 v5, v5
	s_nop 0
	v_fmac_f32_e32 v6, 0xbf317218, v5
	global_store_dword v[2:3], v6, off
	v_mov_b32_e32 v5, v9
	v_fmac_f32_e32 v5, v159, v4
	v_min_f32_e32 v6, 0, v5
	v_mul_f32_e64 v5, |v5|, s14
	v_exp_f32_e32 v5, v5
	s_nop 0
	v_add_f32_e32 v5, 1.0, v5
	v_log_f32_e32 v5, v5
	s_nop 0
	v_fmac_f32_e32 v6, 0xbf317218, v5
	global_store_dword v[2:3], v6, off offset:4
	v_mov_b32_e32 v5, v10
	v_fmac_f32_e32 v5, v160, v4
	v_min_f32_e32 v6, 0, v5
	v_mul_f32_e64 v5, |v5|, s14
	v_exp_f32_e32 v5, v5
	s_nop 0
	v_add_f32_e32 v5, 1.0, v5
	v_log_f32_e32 v5, v5
	s_nop 0
	v_fmac_f32_e32 v6, 0xbf317218, v5
	global_store_dword v[2:3], v6, off offset:8
	v_mov_b32_e32 v5, v11
	v_fmac_f32_e32 v5, v161, v4
	v_min_f32_e32 v6, 0, v5
	v_mul_f32_e64 v5, |v5|, s14
	v_exp_f32_e32 v5, v5
	s_nop 0
	v_add_f32_e32 v5, 1.0, v5
	v_log_f32_e32 v5, v5
	s_nop 0
	v_fmac_f32_e32 v6, 0xbf317218, v5
	global_store_dword v[2:3], v6, off offset:12
	v_mov_b32_e32 v5, v12
	v_fmac_f32_e32 v5, v154, v4
	v_min_f32_e32 v6, 0, v5
	v_mul_f32_e64 v5, |v5|, s14
	v_exp_f32_e32 v5, v5
	s_nop 0
	v_add_f32_e32 v5, 1.0, v5
	v_log_f32_e32 v5, v5
	s_nop 0
	v_fmac_f32_e32 v6, 0xbf317218, v5
	global_store_dword v[2:3], v6, off offset:16
	v_mov_b32_e32 v5, v13
	v_fmac_f32_e32 v5, v155, v4
	v_min_f32_e32 v4, 0, v5
	v_mul_f32_e64 v5, |v5|, s14
	v_exp_f32_e32 v5, v5
	s_nop 0
	v_add_f32_e32 v5, 1.0, v5
	v_log_f32_e32 v5, v5
	s_nop 0
	v_fmac_f32_e32 v4, 0xbf317218, v5
	global_store_dword v[2:3], v4, off offset:20
	v_mov_b32_e32 v5, v8
	v_add_u32_e32 v2, 48, v18
	v_and_b32_e32 v3, 0xff, v2
	v_lshl_add_u32 v3, v3, 2, s12
	ds_read_b32 v4, v3
	v_ashrrev_i32_e32 v3, 31, v2
	v_lshlrev_b64 v[2:3], 5, v[2:3]
	v_lshl_add_u64 v[2:3], s[20:21], 0, v[2:3]
	s_waitcnt lgkmcnt(0)
	v_fmac_f32_e32 v5, v142, v4
	v_min_f32_e32 v6, 0, v5
	v_mul_f32_e64 v5, |v5|, s14
	v_exp_f32_e32 v5, v5
	s_nop 0
	v_add_f32_e32 v5, 1.0, v5
	v_log_f32_e32 v5, v5
	s_nop 0
	v_fmac_f32_e32 v6, 0xbf317218, v5
	global_store_dword v[2:3], v6, off
	v_mov_b32_e32 v5, v9
	v_fmac_f32_e32 v5, v143, v4
	v_min_f32_e32 v6, 0, v5
	v_mul_f32_e64 v5, |v5|, s14
	v_exp_f32_e32 v5, v5
	s_nop 0
	v_add_f32_e32 v5, 1.0, v5
	v_log_f32_e32 v5, v5
	s_nop 0
	v_fmac_f32_e32 v6, 0xbf317218, v5
	global_store_dword v[2:3], v6, off offset:4
	v_mov_b32_e32 v5, v10
	v_fmac_f32_e32 v5, v144, v4
	v_min_f32_e32 v6, 0, v5
	v_mul_f32_e64 v5, |v5|, s14
	v_exp_f32_e32 v5, v5
	s_nop 0
	v_add_f32_e32 v5, 1.0, v5
	v_log_f32_e32 v5, v5
	s_nop 0
	v_fmac_f32_e32 v6, 0xbf317218, v5
	global_store_dword v[2:3], v6, off offset:8
	v_mov_b32_e32 v5, v11
	v_fmac_f32_e32 v5, v145, v4
	v_min_f32_e32 v6, 0, v5
	v_mul_f32_e64 v5, |v5|, s14
	v_exp_f32_e32 v5, v5
	s_nop 0
	v_add_f32_e32 v5, 1.0, v5
	v_log_f32_e32 v5, v5
	s_nop 0
	v_fmac_f32_e32 v6, 0xbf317218, v5
	global_store_dword v[2:3], v6, off offset:12
	v_mov_b32_e32 v5, v12
	v_fmac_f32_e32 v5, v138, v4
	v_min_f32_e32 v6, 0, v5
	v_mul_f32_e64 v5, |v5|, s14
	v_exp_f32_e32 v5, v5
	s_nop 0
	v_add_f32_e32 v5, 1.0, v5
	v_log_f32_e32 v5, v5
	s_nop 0
	v_fmac_f32_e32 v6, 0xbf317218, v5
	global_store_dword v[2:3], v6, off offset:16
	v_mov_b32_e32 v5, v13
	v_fmac_f32_e32 v5, v139, v4
	v_min_f32_e32 v4, 0, v5
	v_mul_f32_e64 v5, |v5|, s14
	v_exp_f32_e32 v5, v5
	s_nop 0
	v_add_f32_e32 v5, 1.0, v5
	v_log_f32_e32 v5, v5
	s_nop 0
	v_fmac_f32_e32 v4, 0xbf317218, v5
	global_store_dword v[2:3], v4, off offset:20
	v_mov_b32_e32 v5, v8
	v_add_u32_e32 v2, 0x80, v18
	v_and_b32_e32 v3, 0xff, v2
	v_lshl_add_u32 v3, v3, 2, s12
	ds_read_b32 v4, v3
	v_ashrrev_i32_e32 v3, 31, v2
	v_lshlrev_b64 v[2:3], 5, v[2:3]
	v_lshl_add_u64 v[2:3], s[20:21], 0, v[2:3]
	s_waitcnt lgkmcnt(0)
	v_fmac_f32_e32 v5, v126, v4
	v_min_f32_e32 v6, 0, v5
	v_mul_f32_e64 v5, |v5|, s14
	v_exp_f32_e32 v5, v5
	s_nop 0
	v_add_f32_e32 v5, 1.0, v5
	v_log_f32_e32 v5, v5
	s_nop 0
	v_fmac_f32_e32 v6, 0xbf317218, v5
	global_store_dword v[2:3], v6, off
	v_mov_b32_e32 v5, v9
	v_fmac_f32_e32 v5, v127, v4
	v_min_f32_e32 v6, 0, v5
	v_mul_f32_e64 v5, |v5|, s14
	v_exp_f32_e32 v5, v5
	s_nop 0
	v_add_f32_e32 v5, 1.0, v5
	v_log_f32_e32 v5, v5
	s_nop 0
	v_fmac_f32_e32 v6, 0xbf317218, v5
	global_store_dword v[2:3], v6, off offset:4
	v_mov_b32_e32 v5, v10
	v_fmac_f32_e32 v5, v128, v4
	v_min_f32_e32 v6, 0, v5
	v_mul_f32_e64 v5, |v5|, s14
	v_exp_f32_e32 v5, v5
	s_nop 0
	v_add_f32_e32 v5, 1.0, v5
	v_log_f32_e32 v5, v5
	s_nop 0
	v_fmac_f32_e32 v6, 0xbf317218, v5
	global_store_dword v[2:3], v6, off offset:8
	v_mov_b32_e32 v5, v11
	v_fmac_f32_e32 v5, v129, v4
	v_min_f32_e32 v6, 0, v5
	v_mul_f32_e64 v5, |v5|, s14
	v_exp_f32_e32 v5, v5
	s_nop 0
	v_add_f32_e32 v5, 1.0, v5
	v_log_f32_e32 v5, v5
	s_nop 0
	v_fmac_f32_e32 v6, 0xbf317218, v5
	global_store_dword v[2:3], v6, off offset:12
	v_mov_b32_e32 v5, v12
	v_fmac_f32_e32 v5, v122, v4
	v_min_f32_e32 v6, 0, v5
	v_mul_f32_e64 v5, |v5|, s14
	v_exp_f32_e32 v5, v5
	s_nop 0
	v_add_f32_e32 v5, 1.0, v5
	v_log_f32_e32 v5, v5
	s_nop 0
	v_fmac_f32_e32 v6, 0xbf317218, v5
	global_store_dword v[2:3], v6, off offset:16
	v_mov_b32_e32 v5, v13
	v_fmac_f32_e32 v5, v123, v4
	v_min_f32_e32 v4, 0, v5
	v_mul_f32_e64 v5, |v5|, s14
	v_exp_f32_e32 v5, v5
	s_nop 0
	v_add_f32_e32 v5, 1.0, v5
	v_log_f32_e32 v5, v5
	s_nop 0
	v_fmac_f32_e32 v4, 0xbf317218, v5
	global_store_dword v[2:3], v4, off offset:20
	v_mov_b32_e32 v5, v8
	v_add_u32_e32 v2, 0x90, v18
	v_and_b32_e32 v3, 0xff, v2
	v_lshl_add_u32 v3, v3, 2, s12
	ds_read_b32 v4, v3
	v_ashrrev_i32_e32 v3, 31, v2
	v_lshlrev_b64 v[2:3], 5, v[2:3]
	v_lshl_add_u64 v[2:3], s[20:21], 0, v[2:3]
	s_waitcnt lgkmcnt(0)
; __device__ __forceinline__ float fexp2(float x) { return __builtin_amdgcn_exp2f(x); }
; __device__ __forceinline__ float flog2(float x) { return __builtin_amdgcn_logf(x); }
;     __device__ __forceinline__ void operator()(AccRef acc, const pg8::Unit& u, int wr, int wc, int fr, int fq) const {
;     ...
;         if (G == 78) {
;             if (fq == 0) {
; #pragma unroll
;                 for (int ai = 0; ai < 2; ++ai)
; #pragma unroll
;                     for (int m = 0; m < 4; ++m) {
;                         const int row = row0 + ai * 128 + m * 16;
;                         const float rsr = rst[row & 255];
; #pragma unroll
;                         for (int e = 0; e < 6; ++e) {
;                             const float x = acc[ai][0][m][e >> 2][e & 3] * rsr + fb[e];
;                             const float ls = fminf(x, 0.f) - LN2 * flog2(1.0f + fexp2(-fabsf(x) * LOG2E));
;                             logf[(size_t)row * 8 + e] = ls;
;                         }
;                     }
;             }
	v_fmac_f32_e32 v5, v110, v4
	v_min_f32_e32 v6, 0, v5
	v_mul_f32_e64 v5, |v5|, s14
	v_exp_f32_e32 v5, v5
	s_nop 0
	v_add_f32_e32 v5, 1.0, v5
	v_log_f32_e32 v5, v5
	s_nop 0
	v_fmac_f32_e32 v6, 0xbf317218, v5
	global_store_dword v[2:3], v6, off
	v_mov_b32_e32 v5, v9
	v_fmac_f32_e32 v5, v111, v4
	v_min_f32_e32 v6, 0, v5
	v_mul_f32_e64 v5, |v5|, s14
	v_exp_f32_e32 v5, v5
	s_nop 0
	v_add_f32_e32 v5, 1.0, v5
	v_log_f32_e32 v5, v5
	s_nop 0
	v_fmac_f32_e32 v6, 0xbf317218, v5
	global_store_dword v[2:3], v6, off offset:4
	v_mov_b32_e32 v5, v10
	v_fmac_f32_e32 v5, v112, v4
	v_min_f32_e32 v6, 0, v5
	v_mul_f32_e64 v5, |v5|, s14
	v_exp_f32_e32 v5, v5
	s_nop 0
	v_add_f32_e32 v5, 1.0, v5
	v_log_f32_e32 v5, v5
	s_nop 0
	v_fmac_f32_e32 v6, 0xbf317218, v5
	global_store_dword v[2:3], v6, off offset:8
	v_mov_b32_e32 v5, v11
	v_fmac_f32_e32 v5, v113, v4
	v_min_f32_e32 v6, 0, v5
	v_mul_f32_e64 v5, |v5|, s14
	v_exp_f32_e32 v5, v5
	s_nop 0
	v_add_f32_e32 v5, 1.0, v5
	v_log_f32_e32 v5, v5
	s_nop 0
	v_fmac_f32_e32 v6, 0xbf317218, v5
	global_store_dword v[2:3], v6, off offset:12
	v_mov_b32_e32 v5, v12
	v_fmac_f32_e32 v5, v106, v4
	v_min_f32_e32 v6, 0, v5
	v_mul_f32_e64 v5, |v5|, s14
	v_exp_f32_e32 v5, v5
	s_nop 0
	v_add_f32_e32 v5, 1.0, v5
	v_log_f32_e32 v5, v5
	s_nop 0
	v_fmac_f32_e32 v6, 0xbf317218, v5
	global_store_dword v[2:3], v6, off offset:16
	v_mov_b32_e32 v5, v13
	v_fmac_f32_e32 v5, v107, v4
	v_min_f32_e32 v4, 0, v5
	v_mul_f32_e64 v5, |v5|, s14
	v_exp_f32_e32 v5, v5
	s_nop 0
	v_add_f32_e32 v5, 1.0, v5
	v_log_f32_e32 v5, v5
	s_nop 0
	v_fmac_f32_e32 v4, 0xbf317218, v5
	global_store_dword v[2:3], v4, off offset:20
	v_mov_b32_e32 v5, v8
	v_add_u32_e32 v2, 0xa0, v18
	v_and_b32_e32 v3, 0xff, v2
	v_lshl_add_u32 v3, v3, 2, s12
	ds_read_b32 v4, v3
	v_ashrrev_i32_e32 v3, 31, v2
	v_lshlrev_b64 v[2:3], 5, v[2:3]
	v_lshl_add_u64 v[2:3], s[20:21], 0, v[2:3]
	s_waitcnt lgkmcnt(0)
	v_fmac_f32_e32 v5, v94, v4
	v_min_f32_e32 v6, 0, v5
	v_mul_f32_e64 v5, |v5|, s14
	v_exp_f32_e32 v5, v5
	s_nop 0
	v_add_f32_e32 v5, 1.0, v5
	v_log_f32_e32 v5, v5
	s_nop 0
	v_fmac_f32_e32 v6, 0xbf317218, v5
	global_store_dword v[2:3], v6, off
	v_mov_b32_e32 v5, v9
	v_fmac_f32_e32 v5, v95, v4
	v_min_f32_e32 v6, 0, v5
	v_mul_f32_e64 v5, |v5|, s14
	v_exp_f32_e32 v5, v5
	s_nop 0
	v_add_f32_e32 v5, 1.0, v5
	v_log_f32_e32 v5, v5
	s_nop 0
	v_fmac_f32_e32 v6, 0xbf317218, v5
	global_store_dword v[2:3], v6, off offset:4
	v_mov_b32_e32 v5, v10
	v_fmac_f32_e32 v5, v96, v4
	v_min_f32_e32 v6, 0, v5
	v_mul_f32_e64 v5, |v5|, s14
	v_exp_f32_e32 v5, v5
	s_nop 0
	v_add_f32_e32 v5, 1.0, v5
	v_log_f32_e32 v5, v5
	s_nop 0
	v_fmac_f32_e32 v6, 0xbf317218, v5
	global_store_dword v[2:3], v6, off offset:8
	v_mov_b32_e32 v5, v11
	v_fmac_f32_e32 v5, v97, v4
	v_min_f32_e32 v6, 0, v5
	v_mul_f32_e64 v5, |v5|, s14
	v_exp_f32_e32 v5, v5
	s_nop 0
	v_add_f32_e32 v5, 1.0, v5
	v_log_f32_e32 v5, v5
	s_nop 0
	v_fmac_f32_e32 v6, 0xbf317218, v5
	global_store_dword v[2:3], v6, off offset:12
	v_mov_b32_e32 v5, v12
	v_fmac_f32_e32 v5, v90, v4
	v_min_f32_e32 v6, 0, v5
	v_mul_f32_e64 v5, |v5|, s14
	v_exp_f32_e32 v5, v5
	s_nop 0
	v_add_f32_e32 v5, 1.0, v5
	v_log_f32_e32 v5, v5
	s_nop 0
	v_fmac_f32_e32 v6, 0xbf317218, v5
	global_store_dword v[2:3], v6, off offset:16
	v_mov_b32_e32 v5, v13
	v_fmac_f32_e32 v5, v91, v4
	v_min_f32_e32 v4, 0, v5
	v_mul_f32_e64 v5, |v5|, s14
	v_exp_f32_e32 v5, v5
	s_nop 0
	v_add_f32_e32 v5, 1.0, v5
	v_log_f32_e32 v5, v5
	s_nop 0
	v_fmac_f32_e32 v4, 0xbf317218, v5
	global_store_dword v[2:3], v4, off offset:20
	v_mov_b32_e32 v5, v8
	v_add_u32_e32 v2, 0xb0, v18
	v_and_b32_e32 v3, 0xff, v2
	v_lshl_add_u32 v3, v3, 2, s12
	ds_read_b32 v4, v3
	v_ashrrev_i32_e32 v3, 31, v2
	v_lshlrev_b64 v[2:3], 5, v[2:3]
	v_lshl_add_u64 v[2:3], s[20:21], 0, v[2:3]
	s_waitcnt lgkmcnt(0)
	v_fmac_f32_e32 v5, v78, v4
	v_min_f32_e32 v6, 0, v5
	v_mul_f32_e64 v5, |v5|, s14
	v_exp_f32_e32 v5, v5
	s_nop 0
	v_add_f32_e32 v5, 1.0, v5
	v_log_f32_e32 v5, v5
	s_nop 0
	v_fmac_f32_e32 v6, 0xbf317218, v5
	global_store_dword v[2:3], v6, off
	v_mov_b32_e32 v5, v9
	v_fmac_f32_e32 v5, v79, v4
	v_min_f32_e32 v6, 0, v5
	v_mul_f32_e64 v5, |v5|, s14
	v_exp_f32_e32 v5, v5
	s_nop 0
	v_add_f32_e32 v5, 1.0, v5
	v_log_f32_e32 v5, v5
	s_nop 0
	v_fmac_f32_e32 v6, 0xbf317218, v5
	global_store_dword v[2:3], v6, off offset:4
	v_mov_b32_e32 v5, v10
	v_fmac_f32_e32 v5, v80, v4
	v_min_f32_e32 v6, 0, v5
	v_mul_f32_e64 v5, |v5|, s14
	v_exp_f32_e32 v5, v5
	s_nop 0
	v_add_f32_e32 v5, 1.0, v5
	v_log_f32_e32 v5, v5
	s_nop 0
	v_fmac_f32_e32 v6, 0xbf317218, v5
	global_store_dword v[2:3], v6, off offset:8
	v_mov_b32_e32 v5, v11
	v_fmac_f32_e32 v5, v81, v4
	v_min_f32_e32 v6, 0, v5
	v_mul_f32_e64 v5, |v5|, s14
	v_exp_f32_e32 v5, v5
	s_nop 0
	v_add_f32_e32 v5, 1.0, v5
	v_log_f32_e32 v5, v5
	s_nop 0
	v_fmac_f32_e32 v6, 0xbf317218, v5
	global_store_dword v[2:3], v6, off offset:12
	v_mov_b32_e32 v5, v12
	v_fmac_f32_e32 v5, v74, v4
	v_min_f32_e32 v6, 0, v5
	v_mul_f32_e64 v5, |v5|, s14
	v_exp_f32_e32 v5, v5
	s_nop 0
	v_add_f32_e32 v5, 1.0, v5
	v_log_f32_e32 v5, v5
	s_nop 0
	v_fmac_f32_e32 v6, 0xbf317218, v5
	global_store_dword v[2:3], v6, off offset:16
	v_mov_b32_e32 v5, v13
	v_fmac_f32_e32 v5, v75, v4
	v_min_f32_e32 v4, 0, v5
	v_mul_f32_e64 v5, |v5|, s14
	v_exp_f32_e32 v5, v5
	s_nop 0
	v_add_f32_e32 v5, 1.0, v5
	v_log_f32_e32 v5, v5
	s_nop 0
	v_fmac_f32_e32 v4, 0xbf317218, v5
	global_store_dword v[2:3], v4, off offset:20
